# P2 softmax instruction selection: packed f32 logit fma/sub/rowsum, single bias-table base, permlane16/32_swap reductions instead of ds_bpermute
# speedup vs baseline: 1.0059x; 1.0059x over previous
; #define LAS __attribute__((address_space(3)))
;     ...
;     LAS const float* tb = tbl + (kstart + 4 * g - qrel + TBL / 2);
;     float m = NEG;
;     {
;         float tv[2][8];
; #pragma unroll
;         for (int i = 0; i < 8; ++i) tv[0][i] = tb[16 * (i >> 2) + (i & 3)];
; #pragma unroll
;         for (int tp = 0; tp < NT / 2; ++tp) { const int b = tp & 1;
;             if (tp + 1 < NT / 2) {
; #pragma unroll
;                 for (int i = 0; i < 8; ++i) tv[b ^ 1][i] = tb[16 * (2 * (tp + 1) + (i >> 2)) + (i & 3)]; }
;             __builtin_amdgcn_sched_barrier(0);
; #pragma unroll
;             for (int i = 0; i < 8; ++i) { const int t = 2 * tp + (i >> 2), r = i & 3; const float v = s[t][r] * C + tv[b][i]; s[t][r] = v; m = fmaxf(m, v); }
;             __builtin_amdgcn_sched_barrier(0);
;         }
;     }
.LBB0_246:
	s_mulk_i32 s1, 0xa00
	s_add_i32 s1, s1, 0
	v_or_b32_e32 v158, s0, v144
	s_add_i32 s1, s1, 0x1c800
	v_sub_u32_e32 v158, v205, v158
	v_lshl_add_u32 v177, v158, 2, s1
	ds_read2_b32 v[172:173], v177 offset0:192 offset1:193
	ds_read2_b32 v[170:171], v177 offset0:194 offset1:195
	ds_read2_b32 v[168:169], v177 offset0:208 offset1:209
	ds_read2_b32 v[166:167], v177 offset0:210 offset1:211
	ds_read2_b32 v[164:165], v177 offset0:224 offset1:225
	ds_read2_b32 v[162:163], v177 offset0:226 offset1:227
	ds_read2_b32 v[160:161], v177 offset0:240 offset1:241
	ds_read2_b32 v[158:159], v177 offset0:242 offset1:243
	v_add_u32_e32 v20, s0, v201
	v_mov_b64_e32 v[156:157], s[16:17]
	s_movk_i32 s0, 0x300
	v_mad_i64_i32 v[156:157], s[0:1], v20, s0, v[156:157]
	s_lshl_b32 s0, s64, 6
	s_ashr_i32 s1, s0, 31
	v_mul_f32_e32 v176, 0x3fb8aa3b, v204
	v_lshl_add_u64 v[156:157], v[156:157], 0, s[0:1]
	s_mov_b32 s0, 0x3e38aa3b
	s_mov_b32 s1, s0
	v_add_u32_e32 v196, 0x400, v177
	s_waitcnt lgkmcnt(7)
	v_pk_fma_f32 v[172:173], v[140:141], s[0:1], v[172:173] op_sel_hi:[1,0,1]
	s_waitcnt lgkmcnt(6)
	v_pk_fma_f32 v[170:171], v[142:143], s[0:1], v[170:171] op_sel_hi:[1,0,1]
	v_max3_f32 v20, v172, s81, v173
	s_waitcnt lgkmcnt(5)
	v_pk_fma_f32 v[168:169], v[136:137], s[0:1], v[168:169] op_sel_hi:[1,0,1]
	v_max3_f32 v20, v20, v170, v171
	s_waitcnt lgkmcnt(4)
	v_pk_fma_f32 v[166:167], v[138:139], s[0:1], v[166:167] op_sel_hi:[1,0,1]
	v_max3_f32 v20, v20, v168, v169
	ds_read2_b32 v[142:143], v196 offset0:0 offset1:1
	ds_read2_b32 v[140:141], v196 offset0:2 offset1:3
	ds_read2_b32 v[138:139], v196 offset0:16 offset1:17
	ds_read2_b32 v[136:137], v196 offset0:18 offset1:19
	s_waitcnt lgkmcnt(7)
	v_pk_fma_f32 v[164:165], v[132:133], s[0:1], v[164:165] op_sel_hi:[1,0,1]
	v_max3_f32 v20, v20, v166, v167
	s_waitcnt lgkmcnt(6)
	v_pk_fma_f32 v[162:163], v[134:135], s[0:1], v[162:163] op_sel_hi:[1,0,1]
	v_max3_f32 v20, v20, v164, v165
	s_waitcnt lgkmcnt(5)
	v_pk_fma_f32 v[160:161], v[128:129], s[0:1], v[160:161] op_sel_hi:[1,0,1]
	v_max3_f32 v20, v20, v162, v163
	s_waitcnt lgkmcnt(4)
	v_pk_fma_f32 v[158:159], v[130:131], s[0:1], v[158:159] op_sel_hi:[1,0,1]
	v_max3_f32 v20, v20, v160, v161
	ds_read2_b32 v[134:135], v196 offset0:32 offset1:33
	ds_read2_b32 v[132:133], v196 offset0:34 offset1:35
	ds_read2_b32 v[130:131], v196 offset0:48 offset1:49
	ds_read2_b32 v[128:129], v196 offset0:50 offset1:51
	s_waitcnt lgkmcnt(7)
	v_pk_fma_f32 v[142:143], v[124:125], s[0:1], v[142:143] op_sel_hi:[1,0,1]
	v_max3_f32 v20, v20, v158, v159
	s_waitcnt lgkmcnt(6)
	v_pk_fma_f32 v[140:141], v[126:127], s[0:1], v[140:141] op_sel_hi:[1,0,1]
	v_max3_f32 v20, v20, v142, v143
	s_waitcnt lgkmcnt(5)
	v_pk_fma_f32 v[138:139], v[120:121], s[0:1], v[138:139] op_sel_hi:[1,0,1]
	v_max3_f32 v20, v20, v140, v141
	s_waitcnt lgkmcnt(4)
	v_pk_fma_f32 v[136:137], v[122:123], s[0:1], v[136:137] op_sel_hi:[1,0,1]
	v_max3_f32 v20, v20, v138, v139
	ds_read2_b32 v[126:127], v196 offset0:64 offset1:65
	ds_read2_b32 v[124:125], v196 offset0:66 offset1:67
	ds_read2_b32 v[122:123], v196 offset0:80 offset1:81
	ds_read2_b32 v[120:121], v196 offset0:82 offset1:83
	s_waitcnt lgkmcnt(7)
	v_pk_fma_f32 v[134:135], v[116:117], s[0:1], v[134:135] op_sel_hi:[1,0,1]
	v_max3_f32 v20, v20, v136, v137
	s_waitcnt lgkmcnt(6)
	v_pk_fma_f32 v[132:133], v[118:119], s[0:1], v[132:133] op_sel_hi:[1,0,1]
	v_max3_f32 v20, v20, v134, v135
	s_waitcnt lgkmcnt(5)
	v_pk_fma_f32 v[130:131], v[88:89], s[0:1], v[130:131] op_sel_hi:[1,0,1]
	v_max3_f32 v20, v20, v132, v133
	s_waitcnt lgkmcnt(4)
	v_pk_fma_f32 v[128:129], v[90:91], s[0:1], v[128:129] op_sel_hi:[1,0,1]
	v_max3_f32 v20, v20, v130, v131
	ds_read2_b32 v[118:119], v196 offset0:96 offset1:97
	ds_read2_b32 v[116:117], v196 offset0:98 offset1:99
	ds_read2_b32 v[90:91], v196 offset0:112 offset1:113
	ds_read2_b32 v[88:89], v196 offset0:114 offset1:115
	s_waitcnt lgkmcnt(7)
	v_pk_fma_f32 v[126:127], v[84:85], s[0:1], v[126:127] op_sel_hi:[1,0,1]
	v_max3_f32 v20, v20, v128, v129
	s_waitcnt lgkmcnt(6)
	v_pk_fma_f32 v[124:125], v[86:87], s[0:1], v[124:125] op_sel_hi:[1,0,1]
	v_max3_f32 v20, v20, v126, v127
	s_waitcnt lgkmcnt(5)
	v_pk_fma_f32 v[122:123], v[80:81], s[0:1], v[122:123] op_sel_hi:[1,0,1]
	v_max3_f32 v20, v20, v124, v125
	s_waitcnt lgkmcnt(4)
	v_pk_fma_f32 v[120:121], v[82:83], s[0:1], v[120:121] op_sel_hi:[1,0,1]
	v_max3_f32 v20, v20, v122, v123
	ds_read2_b32 v[86:87], v196 offset0:128 offset1:129
	ds_read2_b32 v[84:85], v196 offset0:130 offset1:131
	ds_read2_b32 v[82:83], v196 offset0:144 offset1:145
	ds_read2_b32 v[80:81], v196 offset0:146 offset1:147
	s_waitcnt lgkmcnt(7)
	v_pk_fma_f32 v[118:119], v[76:77], s[0:1], v[118:119] op_sel_hi:[1,0,1]
	v_max3_f32 v20, v20, v120, v121
	s_waitcnt lgkmcnt(6)
	v_pk_fma_f32 v[116:117], v[78:79], s[0:1], v[116:117] op_sel_hi:[1,0,1]
	v_max3_f32 v20, v20, v118, v119
	s_waitcnt lgkmcnt(5)
	v_pk_fma_f32 v[90:91], v[72:73], s[0:1], v[90:91] op_sel_hi:[1,0,1]
	v_max3_f32 v20, v20, v116, v117
	s_waitcnt lgkmcnt(4)
	v_pk_fma_f32 v[88:89], v[74:75], s[0:1], v[88:89] op_sel_hi:[1,0,1]
	v_max3_f32 v20, v20, v90, v91
	ds_read2_b32 v[78:79], v196 offset0:160 offset1:161
	ds_read2_b32 v[76:77], v196 offset0:162 offset1:163
	ds_read2_b32 v[74:75], v196 offset0:176 offset1:177
	ds_read2_b32 v[72:73], v196 offset0:178 offset1:179
	s_waitcnt lgkmcnt(7)
	v_pk_fma_f32 v[86:87], v[68:69], s[0:1], v[86:87] op_sel_hi:[1,0,1]
	v_max3_f32 v20, v20, v88, v89
	s_waitcnt lgkmcnt(6)
	v_pk_fma_f32 v[84:85], v[70:71], s[0:1], v[84:85] op_sel_hi:[1,0,1]
	v_max3_f32 v20, v20, v86, v87
	s_waitcnt lgkmcnt(5)
	v_pk_fma_f32 v[82:83], v[52:53], s[0:1], v[82:83] op_sel_hi:[1,0,1]
	v_max3_f32 v20, v20, v84, v85
	s_waitcnt lgkmcnt(4)
;     ...
;             for (int i = 0; i < 8; ++i) { const int t = 2 * tp + (i >> 2), r = i & 3; const float v = s[t][r] * C + tv[b][i]; s[t][r] = v; m = fmaxf(m, v); }
;             __builtin_amdgcn_sched_barrier(0);
;         }
;     }
;     m = fmaxf(m, __shfl_xor(m, 16)); m = fmaxf(m, __shfl_xor(m, 32));
;     if (IS_A) m = fmaxf(m, sink2);
;     float sum = 0.f;
; #pragma unroll
;     for (int t = 0; t < NT; ++t)
; #pragma unroll
;         for (int r = 0; r < 4; ++r) { const float p = __builtin_amdgcn_exp2f(s[t][r] - m); s[t][r] = p; sum += p; }
;     sum += __shfl_xor(sum, 16); sum += __shfl_xor(sum, 32);
;     if (IS_A) sum += __builtin_amdgcn_exp2f(sink2 - m);
	v_pk_fma_f32 v[80:81], v[54:55], s[0:1], v[80:81] op_sel_hi:[1,0,1]
	v_max3_f32 v20, v20, v82, v83
	ds_read2_b32 v[70:71], v196 offset0:192 offset1:193
	ds_read2_b32 v[68:69], v196 offset0:194 offset1:195
	ds_read2_b32 v[54:55], v196 offset0:208 offset1:209
	ds_read2_b32 v[52:53], v196 offset0:210 offset1:211
	s_waitcnt lgkmcnt(7)
	v_pk_fma_f32 v[78:79], v[48:49], s[0:1], v[78:79] op_sel_hi:[1,0,1]
	v_max3_f32 v20, v20, v80, v81
	s_waitcnt lgkmcnt(6)
	v_pk_fma_f32 v[76:77], v[50:51], s[0:1], v[76:77] op_sel_hi:[1,0,1]
	v_max3_f32 v20, v20, v78, v79
	s_waitcnt lgkmcnt(5)
	v_pk_fma_f32 v[74:75], v[16:17], s[0:1], v[74:75] op_sel_hi:[1,0,1]
	v_max3_f32 v20, v20, v76, v77
	s_waitcnt lgkmcnt(4)
	v_pk_fma_f32 v[72:73], v[18:19], s[0:1], v[72:73] op_sel_hi:[1,0,1]
	v_max3_f32 v20, v20, v74, v75
	s_waitcnt lgkmcnt(3)
	v_pk_fma_f32 v[70:71], v[12:13], s[0:1], v[70:71] op_sel_hi:[1,0,1]
	v_max3_f32 v20, v20, v72, v73
	s_waitcnt lgkmcnt(2)
	v_pk_fma_f32 v[68:69], v[14:15], s[0:1], v[68:69] op_sel_hi:[1,0,1]
	v_max3_f32 v20, v20, v70, v71
	s_waitcnt lgkmcnt(1)
	v_pk_fma_f32 v[54:55], v[8:9], s[0:1], v[54:55] op_sel_hi:[1,0,1]
	v_max3_f32 v20, v20, v68, v69
	s_waitcnt lgkmcnt(0)
	v_pk_fma_f32 v[52:53], v[10:11], s[0:1], v[52:53] op_sel_hi:[1,0,1]
	v_max3_f32 v20, v20, v54, v55
	v_max3_f32 v20, v20, v52, v53
	v_mov_b32_e32 v252, v20
	s_nop 1
	v_permlane16_swap_b32_e32 v20, v252
	s_nop 0
	v_max_f32_e32 v20, v20, v252
	v_mov_b32_e32 v252, v20
	s_nop 1
	v_permlane32_swap_b32_e32 v20, v252
	s_nop 0
	v_max3_f32 v8, v20, v252, v176
	v_xor_b32_e32 v250, 0x80000000, v8
	v_pk_add_f32 v[172:173], v[172:173], v[250:251] op_sel_hi:[1,0]
	v_exp_f32_e32 v172, v172
	v_exp_f32_e32 v173, v173
	v_pk_add_f32 v[170:171], v[170:171], v[250:251] op_sel_hi:[1,0]
	v_exp_f32_e32 v170, v170
	v_exp_f32_e32 v171, v171
	v_pk_add_f32 v[168:169], v[168:169], v[250:251] op_sel_hi:[1,0]
	v_exp_f32_e32 v168, v168
	v_exp_f32_e32 v169, v169
	v_pk_add_f32 v[248:249], v[172:173], v[170:171]
	v_pk_add_f32 v[166:167], v[166:167], v[250:251] op_sel_hi:[1,0]
	v_exp_f32_e32 v166, v166
	v_exp_f32_e32 v167, v167
	v_pk_add_f32 v[248:249], v[248:249], v[168:169]
	v_pk_add_f32 v[164:165], v[164:165], v[250:251] op_sel_hi:[1,0]
	v_exp_f32_e32 v164, v164
	v_exp_f32_e32 v165, v165
	v_pk_add_f32 v[248:249], v[248:249], v[166:167]
	v_pk_add_f32 v[162:163], v[162:163], v[250:251] op_sel_hi:[1,0]
	v_exp_f32_e32 v162, v162
	v_exp_f32_e32 v163, v163
	v_pk_add_f32 v[248:249], v[248:249], v[164:165]
	v_pk_add_f32 v[160:161], v[160:161], v[250:251] op_sel_hi:[1,0]
	v_exp_f32_e32 v160, v160
	v_exp_f32_e32 v161, v161
	v_pk_add_f32 v[248:249], v[248:249], v[162:163]
	v_pk_add_f32 v[158:159], v[158:159], v[250:251] op_sel_hi:[1,0]
	v_exp_f32_e32 v158, v158
	v_exp_f32_e32 v159, v159
	v_pk_add_f32 v[248:249], v[248:249], v[160:161]
	v_pk_add_f32 v[142:143], v[142:143], v[250:251] op_sel_hi:[1,0]
	v_exp_f32_e32 v142, v142
	v_exp_f32_e32 v143, v143
	v_pk_add_f32 v[248:249], v[248:249], v[158:159]
	v_pk_add_f32 v[140:141], v[140:141], v[250:251] op_sel_hi:[1,0]
	v_exp_f32_e32 v140, v140
	v_exp_f32_e32 v141, v141
	v_pk_add_f32 v[248:249], v[248:249], v[142:143]
	v_pk_add_f32 v[138:139], v[138:139], v[250:251] op_sel_hi:[1,0]
	v_exp_f32_e32 v138, v138
	v_exp_f32_e32 v139, v139
	v_pk_add_f32 v[248:249], v[248:249], v[140:141]
	v_pk_add_f32 v[136:137], v[136:137], v[250:251] op_sel_hi:[1,0]
	v_exp_f32_e32 v136, v136
	v_exp_f32_e32 v137, v137
	v_pk_add_f32 v[248:249], v[248:249], v[138:139]
	v_pk_add_f32 v[134:135], v[134:135], v[250:251] op_sel_hi:[1,0]
	v_exp_f32_e32 v134, v134
	v_exp_f32_e32 v135, v135
	v_pk_add_f32 v[248:249], v[248:249], v[136:137]
	v_pk_add_f32 v[132:133], v[132:133], v[250:251] op_sel_hi:[1,0]
	v_exp_f32_e32 v132, v132
	v_exp_f32_e32 v133, v133
	v_pk_add_f32 v[248:249], v[248:249], v[134:135]
	v_pk_add_f32 v[130:131], v[130:131], v[250:251] op_sel_hi:[1,0]
	v_exp_f32_e32 v130, v130
	v_exp_f32_e32 v131, v131
	v_pk_add_f32 v[248:249], v[248:249], v[132:133]
	v_pk_add_f32 v[128:129], v[128:129], v[250:251] op_sel_hi:[1,0]
	v_exp_f32_e32 v128, v128
	v_exp_f32_e32 v129, v129
	v_pk_add_f32 v[248:249], v[248:249], v[130:131]
	v_pk_add_f32 v[126:127], v[126:127], v[250:251] op_sel_hi:[1,0]
	v_exp_f32_e32 v176, v126
	v_exp_f32_e32 v177, v127
	v_pk_add_f32 v[248:249], v[248:249], v[128:129]
	v_pk_add_f32 v[124:125], v[124:125], v[250:251] op_sel_hi:[1,0]
	v_exp_f32_e32 v206, v124
	v_exp_f32_e32 v207, v125
	v_pk_add_f32 v[248:249], v[248:249], v[176:177]
	v_pk_add_f32 v[122:123], v[122:123], v[250:251] op_sel_hi:[1,0]
	v_exp_f32_e32 v208, v122
	v_exp_f32_e32 v209, v123
	v_pk_add_f32 v[248:249], v[248:249], v[206:207]
	v_pk_add_f32 v[120:121], v[120:121], v[250:251] op_sel_hi:[1,0]
	v_exp_f32_e32 v210, v120
	v_exp_f32_e32 v211, v121
	v_pk_add_f32 v[248:249], v[248:249], v[208:209]
	v_pk_add_f32 v[118:119], v[118:119], v[250:251] op_sel_hi:[1,0]
	v_exp_f32_e32 v212, v118
	v_exp_f32_e32 v213, v119
	v_pk_add_f32 v[248:249], v[248:249], v[210:211]
	v_pk_add_f32 v[116:117], v[116:117], v[250:251] op_sel_hi:[1,0]
	v_exp_f32_e32 v214, v116
	v_exp_f32_e32 v215, v117
	v_pk_add_f32 v[248:249], v[248:249], v[212:213]
	v_pk_add_f32 v[90:91], v[90:91], v[250:251] op_sel_hi:[1,0]
	v_exp_f32_e32 v216, v90
	v_exp_f32_e32 v217, v91
	v_pk_add_f32 v[248:249], v[248:249], v[214:215]
	v_pk_add_f32 v[88:89], v[88:89], v[250:251] op_sel_hi:[1,0]
	v_exp_f32_e32 v218, v88
	v_exp_f32_e32 v219, v89
	v_pk_add_f32 v[248:249], v[248:249], v[216:217]
	v_pk_add_f32 v[86:87], v[86:87], v[250:251] op_sel_hi:[1,0]
	v_exp_f32_e32 v220, v86
	v_exp_f32_e32 v221, v87
	v_pk_add_f32 v[248:249], v[248:249], v[218:219]
	v_pk_add_f32 v[84:85], v[84:85], v[250:251] op_sel_hi:[1,0]
; #define LAS __attribute__((address_space(3)))
; __device__ __forceinline__ unsigned cvtpk(float lo, float hi) { return pg8::cvt_pk_bf16(lo, hi); }
; __device__ __forceinline__ s16x4 vtr(LAS const unsigned char* p) { return __builtin_bit_cast(s16x4, __builtin_amdgcn_ds_read_tr16_b64_v4i16((LAS s16x4*)p)); }
;     ...
;     for (int t = 0; t < NT; ++t)
; #pragma unroll
;         for (int r = 0; r < 4; ++r) { const float p = __builtin_amdgcn_exp2f(s[t][r] - m); s[t][r] = p; sum += p; }
;     sum += __shfl_xor(sum, 16); sum += __shfl_xor(sum, 32);
;     if (IS_A) sum += __builtin_amdgcn_exp2f(sink2 - m);
;     const float inv = __builtin_amdgcn_rcpf(sum);
;     f32x4 o[4];
; #pragma unroll
;     for (int d = 0; d < 4; ++d) o[d] = (f32x4){0.f, 0.f, 0.f, 0.f};
;     LAS const unsigned char* vp = ldsV + (kstart + 4 * g + (qi >> 2)) * VRS + (qi & 3) * 8;
;     {
;         s16x4 vl[2][4], vh[2][4];
; #pragma unroll
;         for (int d = 0; d < 4; ++d) { vl[0][d] = vtr(vp + d * 32); vh[0][d] = vtr(vp + 16 * VRS + d * 32); }
; #pragma unroll
;         for (int c = 0; c < NCH; ++c) { const int b = c & 1;
;             if (c + 1 < NCH) {
; #pragma unroll
;                 for (int d = 0; d < 4; ++d) { vl[b ^ 1][d] = vtr(vp + (32 * (c + 1)) * VRS + d * 32); vh[b ^ 1][d] = vtr(vp + (32 * (c + 1) + 16) * VRS + d * 32); } }
;             v4u pw; pw.x = cvtpk(s[2 * c][0], s[2 * c][1]); pw.y = cvtpk(s[2 * c][2], s[2 * c][3]); pw.z = cvtpk(s[2 * c + 1][0], s[2 * c + 1][1]); pw.w = cvtpk(s[2 * c + 1][2], s[2 * c + 1][3]);
;             const bf16x8 pb = __builtin_bit_cast(bf16x8, pw);
;             __builtin_amdgcn_sched_barrier(0);
; #pragma unroll
;             for (int d = 0; d < 4; ++d) { const s16x4 lo = vl[b][d], hi = vh[b][d];
;                 const bf16x8 va = (bf16x8){lo[0], lo[1], lo[2], lo[3], hi[0], hi[1], hi[2], hi[3]};
;                 o[d] = __builtin_amdgcn_mfma_f32_16x16x32_bf16(va, pb, o[d], 0, 0, 0); }
	v_exp_f32_e32 v222, v84
	v_exp_f32_e32 v223, v85
	v_pk_add_f32 v[248:249], v[248:249], v[220:221]
	v_pk_add_f32 v[82:83], v[82:83], v[250:251] op_sel_hi:[1,0]
	v_exp_f32_e32 v224, v82
	v_exp_f32_e32 v225, v83
	v_pk_add_f32 v[248:249], v[248:249], v[222:223]
	v_pk_add_f32 v[80:81], v[80:81], v[250:251] op_sel_hi:[1,0]
	v_exp_f32_e32 v226, v80
	v_exp_f32_e32 v227, v81
	v_pk_add_f32 v[248:249], v[248:249], v[224:225]
	v_pk_add_f32 v[78:79], v[78:79], v[250:251] op_sel_hi:[1,0]
	v_exp_f32_e32 v228, v78
	v_exp_f32_e32 v229, v79
	v_pk_add_f32 v[248:249], v[248:249], v[226:227]
	v_pk_add_f32 v[76:77], v[76:77], v[250:251] op_sel_hi:[1,0]
	v_exp_f32_e32 v230, v76
	v_exp_f32_e32 v231, v77
	v_pk_add_f32 v[248:249], v[248:249], v[228:229]
	v_pk_add_f32 v[74:75], v[74:75], v[250:251] op_sel_hi:[1,0]
	v_exp_f32_e32 v232, v74
	v_exp_f32_e32 v233, v75
	v_pk_add_f32 v[248:249], v[248:249], v[230:231]
	v_pk_add_f32 v[72:73], v[72:73], v[250:251] op_sel_hi:[1,0]
	v_exp_f32_e32 v234, v72
	v_exp_f32_e32 v235, v73
	v_pk_add_f32 v[248:249], v[248:249], v[232:233]
	v_pk_add_f32 v[70:71], v[70:71], v[250:251] op_sel_hi:[1,0]
	v_exp_f32_e32 v236, v70
	v_exp_f32_e32 v237, v71
	v_pk_add_f32 v[248:249], v[248:249], v[234:235]
	v_pk_add_f32 v[68:69], v[68:69], v[250:251] op_sel_hi:[1,0]
	v_exp_f32_e32 v242, v68
	v_exp_f32_e32 v243, v69
	v_pk_add_f32 v[248:249], v[248:249], v[236:237]
	v_pk_add_f32 v[54:55], v[54:55], v[250:251] op_sel_hi:[1,0]
	v_exp_f32_e32 v244, v54
	v_exp_f32_e32 v245, v55
	v_pk_add_f32 v[248:249], v[248:249], v[242:243]
	v_pk_add_f32 v[52:53], v[52:53], v[250:251] op_sel_hi:[1,0]
	v_exp_f32_e32 v246, v52
	v_exp_f32_e32 v247, v53
	v_pk_add_f32 v[248:249], v[248:249], v[244:245]
	s_nop 0
	v_pk_add_f32 v[248:249], v[248:249], v[246:247]
	v_add_f32_e32 v239, v248, v249
	v_mov_b32_e32 v252, v239
	v_cvt_pk_bf16_f32 v84, v172, v173
	v_cvt_pk_bf16_f32 v85, v170, v171
	v_permlane16_swap_b32_e32 v239, v252
	s_nop 0
	v_add_f32_e32 v239, v239, v252
	v_mov_b32_e32 v252, v239
	v_cvt_pk_bf16_f32 v86, v168, v169
	v_cvt_pk_bf16_f32 v87, v166, v167
	v_permlane32_swap_b32_e32 v239, v252
	s_nop 0
	v_add_f32_e32 v239, v239, v252
	v_or_b32_e32 v10, v205, v178
	v_mad_u32_u24 v82, v10, s79, v150
	v_add_u32_e32 v205, 0xd800, v82
	ds_read_b64_tr_b16 v[10:11], v82 offset:55296
	ds_read_b64_tr_b16 v[14:15], v82 offset:55328
	ds_read_b64_tr_b16 v[48:49], v82 offset:55360
	ds_read_b64_tr_b16 v[52:53], v82 offset:55392
	ds_read_b64_tr_b16 v[12:13], v82 offset:57856
	ds_read_b64_tr_b16 v[16:17], v82 offset:57888
	ds_read_b64_tr_b16 v[50:51], v82 offset:57920
	ds_read_b64_tr_b16 v[54:55], v82 offset:57952
	ds_read_b64_tr_b16 v[68:69], v82 offset:60416
	ds_read_b64_tr_b16 v[72:73], v82 offset:60448
	ds_read_b64_tr_b16 v[76:77], v82 offset:60480
	ds_read_b64_tr_b16 v[80:81], v82 offset:60512
	ds_read_b64_tr_b16 v[70:71], v82 offset:62976
	ds_read_b64_tr_b16 v[74:75], v82 offset:63008
	ds_read_b64_tr_b16 v[78:79], v82 offset:63040
	ds_read_b64_tr_b16 v[82:83], v82 offset:63072
	s_waitcnt lgkmcnt(11)
	v_mfma_f32_16x16x32_bf16 v[10:13], v[10:13], v[84:87], 0
	s_waitcnt lgkmcnt(10)
	v_mfma_f32_16x16x32_bf16 v[14:17], v[14:17], v[84:87], 0
	s_waitcnt lgkmcnt(9)
	v_mfma_f32_16x16x32_bf16 v[48:51], v[48:51], v[84:87], 0
	s_waitcnt lgkmcnt(8)
	v_mfma_f32_16x16x32_bf16 v[52:55], v[52:55], v[84:87], 0
	ds_read_b64_tr_b16 v[84:85], v205 offset:10240
	ds_read_b64_tr_b16 v[88:89], v205 offset:10272
	ds_read_b64_tr_b16 v[116:117], v205 offset:10304
	ds_read_b64_tr_b16 v[120:121], v205 offset:10336
	ds_read_b64_tr_b16 v[86:87], v205 offset:12800
	ds_read_b64_tr_b16 v[90:91], v205 offset:12832
	ds_read_b64_tr_b16 v[118:119], v205 offset:12864
	ds_read_b64_tr_b16 v[122:123], v205 offset:12896
	v_cvt_pk_bf16_f32 v124, v164, v165
	v_cvt_pk_bf16_f32 v125, v162, v163
	v_cvt_pk_bf16_f32 v126, v160, v161
	v_cvt_pk_bf16_f32 v127, v158, v159
	s_waitcnt lgkmcnt(11)
	s_nop 0
	v_mfma_f32_16x16x32_bf16 v[10:13], v[68:71], v[124:127], v[10:13]
	s_waitcnt lgkmcnt(10)
	v_mfma_f32_16x16x32_bf16 v[14:17], v[72:75], v[124:127], v[14:17]
	s_waitcnt lgkmcnt(9)
	v_mfma_f32_16x16x32_bf16 v[48:51], v[76:79], v[124:127], v[48:51]
	s_waitcnt lgkmcnt(8)
	v_mfma_f32_16x16x32_bf16 v[52:55], v[80:83], v[124:127], v[52:55]
	ds_read_b64_tr_b16 v[68:69], v205 offset:15360
	ds_read_b64_tr_b16 v[72:73], v205 offset:15392
	ds_read_b64_tr_b16 v[76:77], v205 offset:15424
	ds_read_b64_tr_b16 v[80:81], v205 offset:15456
	ds_read_b64_tr_b16 v[70:71], v205 offset:17920
	ds_read_b64_tr_b16 v[74:75], v205 offset:17952
	ds_read_b64_tr_b16 v[78:79], v205 offset:17984
	ds_read_b64_tr_b16 v[82:83], v205 offset:18016
	v_cvt_pk_bf16_f32 v124, v142, v143
	v_cvt_pk_bf16_f32 v125, v140, v141
	v_cvt_pk_bf16_f32 v126, v138, v139
	v_cvt_pk_bf16_f32 v127, v136, v137
	s_waitcnt lgkmcnt(11)
	s_nop 0
	v_mfma_f32_16x16x32_bf16 v[10:13], v[84:87], v[124:127], v[10:13]
	s_waitcnt lgkmcnt(10)
	v_mfma_f32_16x16x32_bf16 v[14:17], v[88:91], v[124:127], v[14:17]
	s_waitcnt lgkmcnt(9)
	v_mfma_f32_16x16x32_bf16 v[48:51], v[116:119], v[124:127], v[48:51]
	s_waitcnt lgkmcnt(8)
	v_mfma_f32_16x16x32_bf16 v[52:55], v[120:123], v[124:127], v[52:55]
	ds_read_b64_tr_b16 v[84:85], v205 offset:20480
	ds_read_b64_tr_b16 v[88:89], v205 offset:20512
	ds_read_b64_tr_b16 v[116:117], v205 offset:20544
	ds_read_b64_tr_b16 v[120:121], v205 offset:20576
	ds_read_b64_tr_b16 v[86:87], v205 offset:23040
	ds_read_b64_tr_b16 v[90:91], v205 offset:23072
	ds_read_b64_tr_b16 v[118:119], v205 offset:23104
	ds_read_b64_tr_b16 v[122:123], v205 offset:23136
	v_cvt_pk_bf16_f32 v124, v134, v135
	v_cvt_pk_bf16_f32 v125, v132, v133
	v_cvt_pk_bf16_f32 v126, v130, v131
	v_cvt_pk_bf16_f32 v127, v128, v129
	s_waitcnt lgkmcnt(11)
; __device__ __forceinline__ unsigned cvtpk(float lo, float hi) { return pg8::cvt_pk_bf16(lo, hi); }
; __device__ __forceinline__ unsigned pk4_fp8(float a, float b, float c, float d) { int r = __builtin_amdgcn_cvt_pk_fp8_f32(a, b, 0, false); r = __builtin_amdgcn_cvt_pk_fp8_f32(c, d, r, true); return (unsigned)r; }
; __device__ __forceinline__ s16x4 vtr(LAS const unsigned char* p) { return __builtin_bit_cast(s16x4, __builtin_amdgcn_ds_read_tr16_b64_v4i16((LAS s16x4*)p)); }
;     ...
;         for (int c = 0; c < NCH; ++c) { const int b = c & 1;
;             if (c + 1 < NCH) {
; #pragma unroll
;                 for (int d = 0; d < 4; ++d) { vl[b ^ 1][d] = vtr(vp + (32 * (c + 1)) * VRS + d * 32); vh[b ^ 1][d] = vtr(vp + (32 * (c + 1) + 16) * VRS + d * 32); } }
;             v4u pw; pw.x = cvtpk(s[2 * c][0], s[2 * c][1]); pw.y = cvtpk(s[2 * c][2], s[2 * c][3]); pw.z = cvtpk(s[2 * c + 1][0], s[2 * c + 1][1]); pw.w = cvtpk(s[2 * c + 1][2], s[2 * c + 1][3]);
;             const bf16x8 pb = __builtin_bit_cast(bf16x8, pw);
;             __builtin_amdgcn_sched_barrier(0);
; #pragma unroll
;             for (int d = 0; d < 4; ++d) { const s16x4 lo = vl[b][d], hi = vh[b][d];
;                 const bf16x8 va = (bf16x8){lo[0], lo[1], lo[2], lo[3], hi[0], hi[1], hi[2], hi[3]};
;                 o[d] = __builtin_amdgcn_mfma_f32_16x16x32_bf16(va, pb, o[d], 0, 0, 0); }
;             __builtin_amdgcn_sched_barrier(0);
;         }
;     }
;     if (IS_A) { const float i8 = inv * 8.f;
; #pragma unroll
;         for (int d = 0; d < 4; ++d) *(unsigned*)((unsigned char*)orow + 16 * d + 4 * g) = pk4_fp8(o[d][0] * i8, o[d][1] * i8, o[d][2] * i8, o[d][3] * i8);
	s_nop 0
	v_mfma_f32_16x16x32_bf16 v[10:13], v[68:71], v[124:127], v[10:13]
	s_waitcnt lgkmcnt(10)
	v_mfma_f32_16x16x32_bf16 v[14:17], v[72:75], v[124:127], v[14:17]
	s_waitcnt lgkmcnt(9)
	v_mfma_f32_16x16x32_bf16 v[48:51], v[76:79], v[124:127], v[48:51]
	s_waitcnt lgkmcnt(8)
	v_mfma_f32_16x16x32_bf16 v[52:55], v[80:83], v[124:127], v[52:55]
	ds_read_b64_tr_b16 v[68:69], v205 offset:25600
	ds_read_b64_tr_b16 v[72:73], v205 offset:25632
	ds_read_b64_tr_b16 v[76:77], v205 offset:25664
	ds_read_b64_tr_b16 v[80:81], v205 offset:25696
	ds_read_b64_tr_b16 v[70:71], v205 offset:28160
	ds_read_b64_tr_b16 v[74:75], v205 offset:28192
	ds_read_b64_tr_b16 v[78:79], v205 offset:28224
	ds_read_b64_tr_b16 v[82:83], v205 offset:28256
	v_cvt_pk_bf16_f32 v124, v176, v177
	v_cvt_pk_bf16_f32 v125, v206, v207
	v_cvt_pk_bf16_f32 v126, v208, v209
	v_cvt_pk_bf16_f32 v127, v210, v211
	s_waitcnt lgkmcnt(11)
	s_nop 0
	v_mfma_f32_16x16x32_bf16 v[10:13], v[84:87], v[124:127], v[10:13]
	s_waitcnt lgkmcnt(10)
	v_mfma_f32_16x16x32_bf16 v[14:17], v[88:91], v[124:127], v[14:17]
	s_waitcnt lgkmcnt(9)
	v_mfma_f32_16x16x32_bf16 v[48:51], v[116:119], v[124:127], v[48:51]
	s_waitcnt lgkmcnt(8)
	v_mfma_f32_16x16x32_bf16 v[52:55], v[120:123], v[124:127], v[52:55]
	ds_read_b64_tr_b16 v[84:85], v205 offset:30720
	ds_read_b64_tr_b16 v[88:89], v205 offset:30752
	ds_read_b64_tr_b16 v[116:117], v205 offset:30784
	ds_read_b64_tr_b16 v[120:121], v205 offset:30816
	ds_read_b64_tr_b16 v[86:87], v205 offset:33280
	ds_read_b64_tr_b16 v[90:91], v205 offset:33312
	ds_read_b64_tr_b16 v[118:119], v205 offset:33344
	ds_read_b64_tr_b16 v[122:123], v205 offset:33376
	v_cvt_pk_bf16_f32 v124, v212, v213
	v_cvt_pk_bf16_f32 v125, v214, v215
	v_cvt_pk_bf16_f32 v126, v216, v217
	v_cvt_pk_bf16_f32 v127, v218, v219
	s_waitcnt lgkmcnt(11)
	s_nop 0
	v_mfma_f32_16x16x32_bf16 v[10:13], v[68:71], v[124:127], v[10:13]
	s_waitcnt lgkmcnt(10)
	v_mfma_f32_16x16x32_bf16 v[14:17], v[72:75], v[124:127], v[14:17]
	s_waitcnt lgkmcnt(9)
	v_mfma_f32_16x16x32_bf16 v[48:51], v[76:79], v[124:127], v[48:51]
	s_waitcnt lgkmcnt(8)
	v_mfma_f32_16x16x32_bf16 v[52:55], v[80:83], v[124:127], v[52:55]
	ds_read_b64_tr_b16 v[68:69], v205 offset:35840
	ds_read_b64_tr_b16 v[72:73], v205 offset:35872
	ds_read_b64_tr_b16 v[76:77], v205 offset:35904
	ds_read_b64_tr_b16 v[80:81], v205 offset:35936
	ds_read_b64_tr_b16 v[70:71], v205 offset:38400
	ds_read_b64_tr_b16 v[74:75], v205 offset:38432
	ds_read_b64_tr_b16 v[78:79], v205 offset:38464
	ds_read_b64_tr_b16 v[82:83], v205 offset:38496
	v_cvt_pk_bf16_f32 v124, v220, v221
	v_cvt_pk_bf16_f32 v125, v222, v223
	v_cvt_pk_bf16_f32 v126, v224, v225
	v_cvt_pk_bf16_f32 v127, v226, v227
	s_waitcnt lgkmcnt(11)
	s_nop 0
	v_mfma_f32_16x16x32_bf16 v[10:13], v[84:87], v[124:127], v[10:13]
	s_waitcnt lgkmcnt(10)
	v_mfma_f32_16x16x32_bf16 v[14:17], v[88:91], v[124:127], v[14:17]
	s_waitcnt lgkmcnt(9)
	v_mfma_f32_16x16x32_bf16 v[48:51], v[116:119], v[124:127], v[48:51]
	s_waitcnt lgkmcnt(8)
	v_mfma_f32_16x16x32_bf16 v[52:55], v[120:123], v[124:127], v[52:55]
	ds_read_b64_tr_b16 v[84:85], v205 offset:40960
	ds_read_b64_tr_b16 v[88:89], v205 offset:40992
	ds_read_b64_tr_b16 v[116:117], v205 offset:41024
	ds_read_b64_tr_b16 v[120:121], v205 offset:41056
	ds_read_b64_tr_b16 v[86:87], v205 offset:43520
	ds_read_b64_tr_b16 v[90:91], v205 offset:43552
	ds_read_b64_tr_b16 v[118:119], v205 offset:43584
	ds_read_b64_tr_b16 v[122:123], v205 offset:43616
	v_cvt_pk_bf16_f32 v124, v228, v229
	v_cvt_pk_bf16_f32 v125, v230, v231
	v_cvt_pk_bf16_f32 v126, v232, v233
	v_cvt_pk_bf16_f32 v127, v234, v235
	s_waitcnt lgkmcnt(11)
	s_nop 0
	v_mfma_f32_16x16x32_bf16 v[10:13], v[68:71], v[124:127], v[10:13]
	s_waitcnt lgkmcnt(10)
	v_mfma_f32_16x16x32_bf16 v[14:17], v[72:75], v[124:127], v[14:17]
	s_waitcnt lgkmcnt(9)
	v_mfma_f32_16x16x32_bf16 v[48:51], v[76:79], v[124:127], v[48:51]
	s_waitcnt lgkmcnt(8)
	v_mfma_f32_16x16x32_bf16 v[52:55], v[80:83], v[124:127], v[52:55]
	s_mov_b32 s0, 0x3fb8aa3b
	v_fma_f32 v8, v204, s0, -v8
	v_exp_f32_e32 v8, v8
	v_cvt_pk_bf16_f32 v68, v236, v237
	v_cvt_pk_bf16_f32 v69, v242, v243
	v_add_f32_e32 v20, v8, v239
	v_cvt_pk_bf16_f32 v70, v244, v245
	v_cvt_pk_bf16_f32 v71, v246, v247
	s_waitcnt lgkmcnt(3)
	s_nop 0
	v_mfma_f32_16x16x32_bf16 v[8:11], v[84:87], v[68:71], v[10:13]
	s_waitcnt lgkmcnt(2)
	v_mfma_f32_16x16x32_bf16 v[12:15], v[88:91], v[68:71], v[14:17]
	s_waitcnt lgkmcnt(1)
	v_mfma_f32_16x16x32_bf16 v[16:19], v[116:119], v[68:71], v[48:51]
	s_waitcnt lgkmcnt(0)
	v_mfma_f32_16x16x32_bf16 v[48:51], v[120:123], v[68:71], v[52:55]
	v_rcp_f32_e32 v20, v20
	s_nop 1
	v_mov_b32_e32 v54, 0
	v_lshl_add_u64 v[52:53], v[156:157], 0, v[148:149]
	s_mov_b64 s[64:65], 0
	v_mul_f32_e32 v20, 0x41000000, v20
	v_mul_f32_e32 v8, v20, v8
	v_mul_f32_e32 v9, v20, v9
	v_cvt_pk_fp8_f32 v54, v8, v9
	v_mul_f32_e32 v8, v20, v12
	v_mul_f32_e32 v9, v20, v13
	v_mov_b32_e32 v12, 0
	v_cvt_pk_fp8_f32 v12, v8, v9
	v_mul_f32_e32 v8, v20, v14
	v_mul_f32_e32 v9, v20, v15
	v_mov_b32_e32 v13, 0
	v_cvt_pk_fp8_f32 v12, v8, v9 op_sel:[0,0,1]
	v_mul_f32_e32 v8, v20, v16
	v_mul_f32_e32 v9, v20, v17
	v_cvt_pk_fp8_f32 v13, v8, v9
	v_mul_f32_e32 v8, v20, v48
	v_mul_f32_e32 v9, v20, v49
	v_mov_b32_e32 v14, 0
	v_mul_f32_e32 v10, v20, v10
	v_mul_f32_e32 v11, v20, v11
	v_cvt_pk_fp8_f32 v14, v8, v9
	v_cvt_pk_fp8_f32 v54, v10, v11 op_sel:[0,0,1]
	v_mul_f32_e32 v10, v20, v18
	v_mul_f32_e32 v11, v20, v19
	v_cvt_pk_fp8_f32 v13, v10, v11 op_sel:[0,0,1]
	v_mul_f32_e32 v8, v20, v50
	v_mul_f32_e32 v9, v20, v51
	v_cvt_pk_fp8_f32 v14, v8, v9 op_sel:[0,0,1]
	global_store_dword v[52:53], v54, off
	global_store_dword v[52:53], v12, off offset:16
	global_store_dword v[52:53], v13, off offset:32
	global_store_dword v[52:53], v14, off offset:48
	s_waitcnt vmcnt(4)

; #define LAS __attribute__((address_space(3)))
;     ...
;     LAS const float* tb = tbl + (kstart + 4 * g - qrel + TBL / 2);
;     float m = NEG;
;     {
;         float tv[2][8];
; #pragma unroll
;         for (int i = 0; i < 8; ++i) tv[0][i] = tb[16 * (i >> 2) + (i & 3)];
; #pragma unroll
;         for (int tp = 0; tp < NT / 2; ++tp) { const int b = tp & 1;
;             if (tp + 1 < NT / 2) {
; #pragma unroll
;                 for (int i = 0; i < 8; ++i) tv[b ^ 1][i] = tb[16 * (2 * (tp + 1) + (i >> 2)) + (i & 3)]; }
;             __builtin_amdgcn_sched_barrier(0);
; #pragma unroll
;             for (int i = 0; i < 8; ++i) { const int t = 2 * tp + (i >> 2), r = i & 3; const float v = s[t][r] * C + tv[b][i]; s[t][r] = v; m = fmaxf(m, v); }
;             __builtin_amdgcn_sched_barrier(0);
;         }
;     }
;     m = fmaxf(m, __shfl_xor(m, 16)); m = fmaxf(m, __shfl_xor(m, 32));
;     if (IS_A) m = fmaxf(m, sink2);
;     float sum = 0.f;
; #pragma unroll
;     for (int t = 0; t < NT; ++t)
; #pragma unroll
;         for (int r = 0; r < 4; ++r) { const float p = __builtin_amdgcn_exp2f(s[t][r] - m); s[t][r] = p; sum += p; }
;     sum += __shfl_xor(sum, 16); sum += __shfl_xor(sum, 32);
;     if (IS_A) sum += __builtin_amdgcn_exp2f(sink2 - m);
.LBB0_252:
	v_and_b32_e32 v20, s91, v89
	v_add_u32_e32 v89, s0, v203
	v_lshl_add_u32 v109, v89, 2, s83
	v_add_u32_e32 v109, 0x400, v109
	ds_read2_b32 v[110:111], v109 offset0:0 offset1:1
	ds_read2_b32 v[112:113], v109 offset0:2 offset1:3
	ds_read2_b32 v[114:115], v109 offset0:16 offset1:17
	ds_read2_b32 v[116:117], v109 offset0:18 offset1:19
	ds_read2_b32 v[118:119], v109 offset0:32 offset1:33
	ds_read2_b32 v[120:121], v109 offset0:34 offset1:35
	ds_read2_b32 v[122:123], v109 offset0:48 offset1:49
	ds_read2_b32 v[124:125], v109 offset0:50 offset1:51
	v_mul_lo_u32 v20, v20, s45
	v_add3_u32 v88, s92, v20, v88
	v_ashrrev_i32_e32 v89, 31, v88
	v_lshl_add_u64 v[88:89], s[62:63], 0, v[88:89]
	v_lshlrev_b64 v[90:91], 9, v[88:89]
	s_mov_b32 s0, 0x3e38aa3b
	s_mov_b32 s1, s0
	s_waitcnt lgkmcnt(7)
	v_pk_fma_f32 v[110:111], v[84:85], s[0:1], v[110:111] op_sel_hi:[1,0,1]
	s_waitcnt lgkmcnt(6)
	v_pk_fma_f32 v[112:113], v[86:87], s[0:1], v[112:113] op_sel_hi:[1,0,1]
	v_max3_f32 v20, v110, s81, v111
	s_waitcnt lgkmcnt(5)
	v_pk_fma_f32 v[114:115], v[80:81], s[0:1], v[114:115] op_sel_hi:[1,0,1]
	v_max3_f32 v20, v20, v112, v113
	s_waitcnt lgkmcnt(4)
	v_pk_fma_f32 v[116:117], v[82:83], s[0:1], v[116:117] op_sel_hi:[1,0,1]
	v_max3_f32 v20, v20, v114, v115
	ds_read2_b32 v[80:81], v109 offset0:64 offset1:65
	ds_read2_b32 v[82:83], v109 offset0:66 offset1:67
	ds_read2_b32 v[84:85], v109 offset0:80 offset1:81
	ds_read2_b32 v[86:87], v109 offset0:82 offset1:83
	s_waitcnt lgkmcnt(7)
	v_pk_fma_f32 v[118:119], v[76:77], s[0:1], v[118:119] op_sel_hi:[1,0,1]
	v_max3_f32 v20, v20, v116, v117
	s_waitcnt lgkmcnt(6)
	v_pk_fma_f32 v[120:121], v[78:79], s[0:1], v[120:121] op_sel_hi:[1,0,1]
	v_max3_f32 v20, v20, v118, v119
	s_waitcnt lgkmcnt(5)
	v_pk_fma_f32 v[122:123], v[72:73], s[0:1], v[122:123] op_sel_hi:[1,0,1]
	v_max3_f32 v20, v20, v120, v121
	s_waitcnt lgkmcnt(4)
	v_pk_fma_f32 v[124:125], v[74:75], s[0:1], v[124:125] op_sel_hi:[1,0,1]
	v_max3_f32 v20, v20, v122, v123
	ds_read2_b32 v[72:73], v109 offset0:96 offset1:97
	ds_read2_b32 v[74:75], v109 offset0:98 offset1:99
	ds_read2_b32 v[76:77], v109 offset0:112 offset1:113
	ds_read2_b32 v[78:79], v109 offset0:114 offset1:115
	s_waitcnt lgkmcnt(7)
	v_pk_fma_f32 v[80:81], v[68:69], s[0:1], v[80:81] op_sel_hi:[1,0,1]
	v_max3_f32 v20, v20, v124, v125
	s_waitcnt lgkmcnt(6)
	v_pk_fma_f32 v[82:83], v[70:71], s[0:1], v[82:83] op_sel_hi:[1,0,1]
	v_max3_f32 v20, v20, v80, v81
	s_waitcnt lgkmcnt(5)
	v_pk_fma_f32 v[84:85], v[52:53], s[0:1], v[84:85] op_sel_hi:[1,0,1]
	v_max3_f32 v20, v20, v82, v83
	s_waitcnt lgkmcnt(4)
	v_pk_fma_f32 v[86:87], v[54:55], s[0:1], v[86:87] op_sel_hi:[1,0,1]
	v_max3_f32 v20, v20, v84, v85
	ds_read2_b32 v[52:53], v109 offset0:128 offset1:129
	ds_read2_b32 v[54:55], v109 offset0:130 offset1:131
	ds_read2_b32 v[68:69], v109 offset0:144 offset1:145
	ds_read2_b32 v[70:71], v109 offset0:146 offset1:147
	s_waitcnt lgkmcnt(7)
	v_pk_fma_f32 v[72:73], v[48:49], s[0:1], v[72:73] op_sel_hi:[1,0,1]
	v_max3_f32 v20, v20, v86, v87
	s_waitcnt lgkmcnt(6)
	v_pk_fma_f32 v[74:75], v[50:51], s[0:1], v[74:75] op_sel_hi:[1,0,1]
	v_max3_f32 v20, v20, v72, v73
	s_waitcnt lgkmcnt(5)
	v_pk_fma_f32 v[76:77], v[16:17], s[0:1], v[76:77] op_sel_hi:[1,0,1]
	v_max3_f32 v20, v20, v74, v75
	s_waitcnt lgkmcnt(4)
	v_pk_fma_f32 v[78:79], v[18:19], s[0:1], v[78:79] op_sel_hi:[1,0,1]
	v_max3_f32 v20, v20, v76, v77
	s_waitcnt lgkmcnt(3)
	v_pk_fma_f32 v[52:53], v[12:13], s[0:1], v[52:53] op_sel_hi:[1,0,1]
	v_max3_f32 v20, v20, v78, v79
	s_waitcnt lgkmcnt(2)
	v_pk_fma_f32 v[54:55], v[14:15], s[0:1], v[54:55] op_sel_hi:[1,0,1]
	v_max3_f32 v20, v20, v52, v53
	s_waitcnt lgkmcnt(1)
	v_pk_fma_f32 v[68:69], v[8:9], s[0:1], v[68:69] op_sel_hi:[1,0,1]
	v_max3_f32 v20, v20, v54, v55
	s_waitcnt lgkmcnt(0)
	v_pk_fma_f32 v[70:71], v[10:11], s[0:1], v[70:71] op_sel_hi:[1,0,1]
	v_max3_f32 v20, v20, v68, v69
	v_max3_f32 v20, v20, v70, v71
	v_mov_b32_e32 v252, v20
	s_nop 1
	v_permlane16_swap_b32_e32 v20, v252
	s_nop 0
	v_max_f32_e32 v20, v20, v252
	v_mov_b32_e32 v252, v20
	s_nop 1
	v_permlane32_swap_b32_e32 v20, v252
	s_nop 0
	v_max_f32_e32 v8, v20, v252
	v_xor_b32_e32 v250, 0x80000000, v8
	v_pk_add_f32 v[110:111], v[110:111], v[250:251] op_sel_hi:[1,0]
	v_exp_f32_e32 v110, v110
	v_exp_f32_e32 v111, v111
	v_pk_add_f32 v[112:113], v[112:113], v[250:251] op_sel_hi:[1,0]
	v_exp_f32_e32 v112, v112
	v_exp_f32_e32 v113, v113
	v_pk_add_f32 v[114:115], v[114:115], v[250:251] op_sel_hi:[1,0]
	v_exp_f32_e32 v114, v114
	v_exp_f32_e32 v115, v115
	v_pk_add_f32 v[248:249], v[110:111], v[112:113]
	v_pk_add_f32 v[116:117], v[116:117], v[250:251] op_sel_hi:[1,0]
	v_exp_f32_e32 v116, v116
	v_exp_f32_e32 v117, v117
	v_pk_add_f32 v[248:249], v[248:249], v[114:115]
	v_pk_add_f32 v[118:119], v[118:119], v[250:251] op_sel_hi:[1,0]
	v_exp_f32_e32 v164, v118
	v_exp_f32_e32 v165, v119
	v_pk_add_f32 v[248:249], v[248:249], v[116:117]
	v_pk_add_f32 v[120:121], v[120:121], v[250:251] op_sel_hi:[1,0]
	v_exp_f32_e32 v166, v120
	v_exp_f32_e32 v167, v121
	v_pk_add_f32 v[248:249], v[248:249], v[164:165]
	v_pk_add_f32 v[122:123], v[122:123], v[250:251] op_sel_hi:[1,0]
	v_exp_f32_e32 v168, v122
	v_exp_f32_e32 v169, v123
	v_pk_add_f32 v[248:249], v[248:249], v[166:167]
	v_pk_add_f32 v[124:125], v[124:125], v[250:251] op_sel_hi:[1,0]
	v_exp_f32_e32 v170, v124
	v_exp_f32_e32 v171, v125
	v_pk_add_f32 v[248:249], v[248:249], v[168:169]
	v_pk_add_f32 v[80:81], v[80:81], v[250:251] op_sel_hi:[1,0]
	v_exp_f32_e32 v172, v80
	v_exp_f32_e32 v173, v81
	v_pk_add_f32 v[248:249], v[248:249], v[170:171]
	v_pk_add_f32 v[82:83], v[82:83], v[250:251] op_sel_hi:[1,0]
	v_exp_f32_e32 v176, v82
	v_exp_f32_e32 v177, v83
; #define LAS __attribute__((address_space(3)))
; __device__ __forceinline__ unsigned cvtpk(float lo, float hi) { return pg8::cvt_pk_bf16(lo, hi); }
; __device__ __forceinline__ s16x4 vtr(LAS const unsigned char* p) { return __builtin_bit_cast(s16x4, __builtin_amdgcn_ds_read_tr16_b64_v4i16((LAS s16x4*)p)); }
;     ...
;     for (int t = 0; t < NT; ++t)
; #pragma unroll
;         for (int r = 0; r < 4; ++r) { const float p = __builtin_amdgcn_exp2f(s[t][r] - m); s[t][r] = p; sum += p; }
;     sum += __shfl_xor(sum, 16); sum += __shfl_xor(sum, 32);
;     if (IS_A) sum += __builtin_amdgcn_exp2f(sink2 - m);
;     const float inv = __builtin_amdgcn_rcpf(sum);
;     f32x4 o[4];
; #pragma unroll
;     for (int d = 0; d < 4; ++d) o[d] = (f32x4){0.f, 0.f, 0.f, 0.f};
;     LAS const unsigned char* vp = ldsV + (kstart + 4 * g + (qi >> 2)) * VRS + (qi & 3) * 8;
;     {
;         s16x4 vl[2][4], vh[2][4];
; #pragma unroll
;         for (int d = 0; d < 4; ++d) { vl[0][d] = vtr(vp + d * 32); vh[0][d] = vtr(vp + 16 * VRS + d * 32); }
; #pragma unroll
;         for (int c = 0; c < NCH; ++c) { const int b = c & 1;
;             if (c + 1 < NCH) {
; #pragma unroll
;                 for (int d = 0; d < 4; ++d) { vl[b ^ 1][d] = vtr(vp + (32 * (c + 1)) * VRS + d * 32); vh[b ^ 1][d] = vtr(vp + (32 * (c + 1) + 16) * VRS + d * 32); } }
;             v4u pw; pw.x = cvtpk(s[2 * c][0], s[2 * c][1]); pw.y = cvtpk(s[2 * c][2], s[2 * c][3]); pw.z = cvtpk(s[2 * c + 1][0], s[2 * c + 1][1]); pw.w = cvtpk(s[2 * c + 1][2], s[2 * c + 1][3]);
;             const bf16x8 pb = __builtin_bit_cast(bf16x8, pw);
;             __builtin_amdgcn_sched_barrier(0);
; #pragma unroll
;             for (int d = 0; d < 4; ++d) { const s16x4 lo = vl[b][d], hi = vh[b][d];
;                 const bf16x8 va = (bf16x8){lo[0], lo[1], lo[2], lo[3], hi[0], hi[1], hi[2], hi[3]};
;                 o[d] = __builtin_amdgcn_mfma_f32_16x16x32_bf16(va, pb, o[d], 0, 0, 0); }
	v_pk_add_f32 v[248:249], v[248:249], v[172:173]
	v_pk_add_f32 v[84:85], v[84:85], v[250:251] op_sel_hi:[1,0]
	v_exp_f32_e32 v204, v84
	v_exp_f32_e32 v205, v85
	v_pk_add_f32 v[248:249], v[248:249], v[176:177]
	v_pk_add_f32 v[86:87], v[86:87], v[250:251] op_sel_hi:[1,0]
	v_exp_f32_e32 v206, v86
	v_exp_f32_e32 v207, v87
	v_pk_add_f32 v[248:249], v[248:249], v[204:205]
	v_pk_add_f32 v[72:73], v[72:73], v[250:251] op_sel_hi:[1,0]
	v_exp_f32_e32 v208, v72
	v_exp_f32_e32 v209, v73
	v_pk_add_f32 v[248:249], v[248:249], v[206:207]
	v_pk_add_f32 v[74:75], v[74:75], v[250:251] op_sel_hi:[1,0]
	v_exp_f32_e32 v210, v74
	v_exp_f32_e32 v211, v75
	v_pk_add_f32 v[248:249], v[248:249], v[208:209]
	v_pk_add_f32 v[76:77], v[76:77], v[250:251] op_sel_hi:[1,0]
	v_exp_f32_e32 v212, v76
	v_exp_f32_e32 v213, v77
	v_pk_add_f32 v[248:249], v[248:249], v[210:211]
	v_pk_add_f32 v[78:79], v[78:79], v[250:251] op_sel_hi:[1,0]
	v_exp_f32_e32 v214, v78
	v_exp_f32_e32 v215, v79
	v_pk_add_f32 v[248:249], v[248:249], v[212:213]
	v_pk_add_f32 v[52:53], v[52:53], v[250:251] op_sel_hi:[1,0]
	v_exp_f32_e32 v216, v52
	v_exp_f32_e32 v217, v53
	v_pk_add_f32 v[248:249], v[248:249], v[214:215]
	v_pk_add_f32 v[54:55], v[54:55], v[250:251] op_sel_hi:[1,0]
	v_exp_f32_e32 v218, v54
	v_exp_f32_e32 v219, v55
	v_pk_add_f32 v[248:249], v[248:249], v[216:217]
	v_pk_add_f32 v[68:69], v[68:69], v[250:251] op_sel_hi:[1,0]
	v_exp_f32_e32 v220, v68
	v_exp_f32_e32 v221, v69
	v_pk_add_f32 v[248:249], v[248:249], v[218:219]
	v_pk_add_f32 v[70:71], v[70:71], v[250:251] op_sel_hi:[1,0]
	v_exp_f32_e32 v222, v70
	v_exp_f32_e32 v223, v71
	v_pk_add_f32 v[248:249], v[248:249], v[220:221]
	s_nop 0
	v_pk_add_f32 v[248:249], v[248:249], v[222:223]
	v_add_f32_e32 v9, v248, v249
	v_mov_b32_e32 v252, v9
	v_cvt_pk_bf16_f32 v84, v110, v111
	v_cvt_pk_bf16_f32 v85, v112, v113
	v_permlane16_swap_b32_e32 v9, v252
	s_nop 0
	v_add_f32_e32 v9, v9, v252
	v_mov_b32_e32 v252, v9
	v_cvt_pk_bf16_f32 v86, v114, v115
	v_cvt_pk_bf16_f32 v87, v116, v117
	v_permlane32_swap_b32_e32 v9, v252
	s_nop 0
	v_add_f32_e32 v9, v9, v252
	v_or_b32_e32 v10, v108, v178
	v_mad_u64_u32 v[18:19], s[0:1], v10, s79, v[150:151]
	ds_read_b64_tr_b16 v[10:11], v18 offset:55296
	ds_read_b64_tr_b16 v[14:15], v18 offset:55328
	ds_read_b64_tr_b16 v[48:49], v18 offset:55360
	ds_read_b64_tr_b16 v[52:53], v18 offset:55392
	ds_read_b64_tr_b16 v[12:13], v18 offset:57856
	ds_read_b64_tr_b16 v[16:17], v18 offset:57888
	ds_read_b64_tr_b16 v[50:51], v18 offset:57920
	ds_read_b64_tr_b16 v[54:55], v18 offset:57952
	ds_read_b64_tr_b16 v[68:69], v18 offset:60416
	ds_read_b64_tr_b16 v[72:73], v18 offset:60448
	ds_read_b64_tr_b16 v[76:77], v18 offset:60480
	ds_read_b64_tr_b16 v[80:81], v18 offset:60512
	ds_read_b64_tr_b16 v[70:71], v18 offset:62976
	ds_read_b64_tr_b16 v[74:75], v18 offset:63008
	ds_read_b64_tr_b16 v[78:79], v18 offset:63040
	ds_read_b64_tr_b16 v[82:83], v18 offset:63072
	v_add_u32_e32 v19, 0xd800, v18
	s_waitcnt lgkmcnt(11)
	v_mfma_f32_16x16x32_bf16 v[10:13], v[10:13], v[84:87], 0
	s_waitcnt lgkmcnt(10)
	v_mfma_f32_16x16x32_bf16 v[14:17], v[14:17], v[84:87], 0
	s_waitcnt lgkmcnt(9)
	v_mfma_f32_16x16x32_bf16 v[48:51], v[48:51], v[84:87], 0
	s_waitcnt lgkmcnt(8)
	v_mfma_f32_16x16x32_bf16 v[52:55], v[52:55], v[84:87], 0
	ds_read_b64_tr_b16 v[84:85], v19 offset:10240
	ds_read_b64_tr_b16 v[108:109], v19 offset:10272
	ds_read_b64_tr_b16 v[112:113], v19 offset:10304
	ds_read_b64_tr_b16 v[116:117], v19 offset:10336
	ds_read_b64_tr_b16 v[86:87], v19 offset:12800
	ds_read_b64_tr_b16 v[110:111], v19 offset:12832
	ds_read_b64_tr_b16 v[114:115], v19 offset:12864
	ds_read_b64_tr_b16 v[118:119], v19 offset:12896
	v_cvt_pk_bf16_f32 v120, v164, v165
	v_cvt_pk_bf16_f32 v121, v166, v167
	v_cvt_pk_bf16_f32 v122, v168, v169
	v_cvt_pk_bf16_f32 v123, v170, v171
	s_waitcnt lgkmcnt(11)
	s_nop 0
	v_mfma_f32_16x16x32_bf16 v[10:13], v[68:71], v[120:123], v[10:13]
	s_waitcnt lgkmcnt(10)
; __device__ __forceinline__ unsigned cvtpk(float lo, float hi) { return pg8::cvt_pk_bf16(lo, hi); }
; __device__ __forceinline__ unsigned pk4_fp8(float a, float b, float c, float d) { int r = __builtin_amdgcn_cvt_pk_fp8_f32(a, b, 0, false); r = __builtin_amdgcn_cvt_pk_fp8_f32(c, d, r, true); return (unsigned)r; }
; __device__ __forceinline__ s16x4 vtr(LAS const unsigned char* p) { return __builtin_bit_cast(s16x4, __builtin_amdgcn_ds_read_tr16_b64_v4i16((LAS s16x4*)p)); }
;     ...
;         for (int c = 0; c < NCH; ++c) { const int b = c & 1;
;             if (c + 1 < NCH) {
; #pragma unroll
;                 for (int d = 0; d < 4; ++d) { vl[b ^ 1][d] = vtr(vp + (32 * (c + 1)) * VRS + d * 32); vh[b ^ 1][d] = vtr(vp + (32 * (c + 1) + 16) * VRS + d * 32); } }
;             v4u pw; pw.x = cvtpk(s[2 * c][0], s[2 * c][1]); pw.y = cvtpk(s[2 * c][2], s[2 * c][3]); pw.z = cvtpk(s[2 * c + 1][0], s[2 * c + 1][1]); pw.w = cvtpk(s[2 * c + 1][2], s[2 * c + 1][3]);
;             const bf16x8 pb = __builtin_bit_cast(bf16x8, pw);
;             __builtin_amdgcn_sched_barrier(0);
; #pragma unroll
;             for (int d = 0; d < 4; ++d) { const s16x4 lo = vl[b][d], hi = vh[b][d];
;                 const bf16x8 va = (bf16x8){lo[0], lo[1], lo[2], lo[3], hi[0], hi[1], hi[2], hi[3]};
;                 o[d] = __builtin_amdgcn_mfma_f32_16x16x32_bf16(va, pb, o[d], 0, 0, 0); }
;             __builtin_amdgcn_sched_barrier(0);
;         }
;     }
;     if (IS_A) { const float i8 = inv * 8.f;
; #pragma unroll
;         for (int d = 0; d < 4; ++d) *(unsigned*)((unsigned char*)orow + 16 * d + 4 * g) = pk4_fp8(o[d][0] * i8, o[d][1] * i8, o[d][2] * i8, o[d][3] * i8);
;     } else {
; #pragma unroll
;         for (int d = 0; d < 4; ++d) { v2u w; w.x = cvtpk(o[d][0] * inv, o[d][1] * inv); w.y = cvtpk(o[d][2] * inv, o[d][3] * inv); if (!(abl & 1) || w.x == 0x12345678u) *(v2u*)(orow + 16 * d + 4 * g) = w; } }
;     if (!IS_A) { if (g == 0 && !(abl & 1)) *lsep = m + __builtin_log2f(sum); }
	v_mfma_f32_16x16x32_bf16 v[14:17], v[72:75], v[120:123], v[14:17]
	s_waitcnt lgkmcnt(9)
	v_mfma_f32_16x16x32_bf16 v[48:51], v[76:79], v[120:123], v[48:51]
	s_waitcnt lgkmcnt(8)
	v_mfma_f32_16x16x32_bf16 v[52:55], v[80:83], v[120:123], v[52:55]
	ds_read_b64_tr_b16 v[68:69], v19 offset:15360
	ds_read_b64_tr_b16 v[72:73], v19 offset:15392
	ds_read_b64_tr_b16 v[76:77], v19 offset:15424
	ds_read_b64_tr_b16 v[80:81], v19 offset:15456
	ds_read_b64_tr_b16 v[70:71], v19 offset:17920
	ds_read_b64_tr_b16 v[74:75], v19 offset:17952
	ds_read_b64_tr_b16 v[78:79], v19 offset:17984
	ds_read_b64_tr_b16 v[82:83], v19 offset:18016
	v_cvt_pk_bf16_f32 v120, v172, v173
	v_cvt_pk_bf16_f32 v121, v176, v177
	v_cvt_pk_bf16_f32 v122, v204, v205
	v_cvt_pk_bf16_f32 v123, v206, v207
	s_waitcnt lgkmcnt(11)
	s_nop 0
	v_mfma_f32_16x16x32_bf16 v[10:13], v[84:87], v[120:123], v[10:13]
	s_waitcnt lgkmcnt(10)
	v_mfma_f32_16x16x32_bf16 v[14:17], v[108:111], v[120:123], v[14:17]
	s_waitcnt lgkmcnt(9)
	v_mfma_f32_16x16x32_bf16 v[48:51], v[112:115], v[120:123], v[48:51]
	s_waitcnt lgkmcnt(8)
	v_mfma_f32_16x16x32_bf16 v[52:55], v[116:119], v[120:123], v[52:55]
	ds_read_b64_tr_b16 v[84:85], v19 offset:20480
	ds_read_b64_tr_b16 v[108:109], v19 offset:20512
	ds_read_b64_tr_b16 v[112:113], v19 offset:20544
	ds_read_b64_tr_b16 v[116:117], v19 offset:20576
	ds_read_b64_tr_b16 v[86:87], v19 offset:23040
	ds_read_b64_tr_b16 v[110:111], v19 offset:23072
	ds_read_b64_tr_b16 v[114:115], v19 offset:23104
	ds_read_b64_tr_b16 v[118:119], v19 offset:23136
	v_cvt_pk_bf16_f32 v120, v208, v209
	v_cvt_pk_bf16_f32 v121, v210, v211
	v_cvt_pk_bf16_f32 v122, v212, v213
	v_cvt_pk_bf16_f32 v123, v214, v215
	s_waitcnt lgkmcnt(11)
	s_nop 0
	v_mfma_f32_16x16x32_bf16 v[10:13], v[68:71], v[120:123], v[10:13]
	s_waitcnt lgkmcnt(10)
	v_mfma_f32_16x16x32_bf16 v[14:17], v[72:75], v[120:123], v[14:17]
	s_waitcnt lgkmcnt(9)
	v_mfma_f32_16x16x32_bf16 v[48:51], v[76:79], v[120:123], v[48:51]
	s_waitcnt lgkmcnt(8)
	v_mfma_f32_16x16x32_bf16 v[52:55], v[80:83], v[120:123], v[52:55]
	v_cvt_pk_bf16_f32 v68, v216, v217
	v_cvt_pk_bf16_f32 v69, v218, v219
	v_cvt_pk_bf16_f32 v70, v220, v221
	v_cvt_pk_bf16_f32 v71, v222, v223
	s_waitcnt lgkmcnt(3)
	s_nop 0
	v_mfma_f32_16x16x32_bf16 v[10:13], v[84:87], v[68:71], v[10:13]
	s_waitcnt lgkmcnt(2)
	v_mfma_f32_16x16x32_bf16 v[14:17], v[108:111], v[68:71], v[14:17]
	s_waitcnt lgkmcnt(1)
	v_mfma_f32_16x16x32_bf16 v[48:51], v[112:115], v[68:71], v[48:51]
	s_waitcnt lgkmcnt(0)
	v_mfma_f32_16x16x32_bf16 v[52:55], v[116:119], v[68:71], v[52:55]
	v_rcp_f32_e32 v18, v9
	v_lshl_add_u64 v[68:69], v[22:23], 0, v[90:91]
	v_pk_mul_f32 v[10:11], v[18:19], v[10:11] op_sel_hi:[0,1]
	v_pk_mul_f32 v[12:13], v[18:19], v[12:13] op_sel_hi:[0,1]
	v_cvt_pk_bf16_f32 v10, v10, v11
	v_cvt_pk_bf16_f32 v11, v12, v13
	global_store_dwordx2 v[68:69], v[10:11], off
	v_pk_mul_f32 v[10:11], v[18:19], v[14:15] op_sel_hi:[0,1]
	v_pk_mul_f32 v[12:13], v[18:19], v[16:17] op_sel_hi:[0,1]
	v_cvt_pk_bf16_f32 v10, v10, v11
	v_cvt_pk_bf16_f32 v11, v12, v13
	global_store_dwordx2 v[68:69], v[10:11], off offset:32
	v_pk_mul_f32 v[10:11], v[18:19], v[48:49] op_sel_hi:[0,1]
	v_pk_mul_f32 v[12:13], v[18:19], v[50:51] op_sel_hi:[0,1]
	v_cvt_pk_bf16_f32 v10, v10, v11
	v_cvt_pk_bf16_f32 v11, v12, v13
	global_store_dwordx2 v[68:69], v[10:11], off offset:64
	v_pk_mul_f32 v[10:11], v[18:19], v[52:53] op_sel_hi:[0,1]
	v_pk_mul_f32 v[12:13], v[18:19], v[54:55] op_sel_hi:[0,1]
	v_cvt_pk_bf16_f32 v10, v10, v11
	v_cvt_pk_bf16_f32 v11, v12, v13
	global_store_dwordx2 v[68:69], v[10:11], off offset:96
	s_and_saveexec_b64 s[6:7], s[4:5]
	s_cbranch_execz .LBB0_239
	s_mov_b32 s0, 0x800000
	v_cmp_gt_f32_e32 vcc, s0, v9
	s_nop 1
	v_cndmask_b32_e64 v10, 0, 32, vcc
	v_ldexp_f32 v9, v9, v10
	v_log_f32_e32 v9, v9
	v_cndmask_b32_e32 v12, 0, v200, vcc
	v_lshl_add_u64 v[10:11], v[88:89], 4, s[60:61]
	v_sub_f32_e32 v9, v9, v12
	v_add_f32_e32 v8, v8, v9
	global_store_dword v[10:11], v8, off
	s_branch .LBB0_239
